# non-temporal hint on the first row pass input loads (x read once; keeps the bf16 h rows cache-resident for the z GEMM)
# speedup vs baseline: 1.0311x; 1.0036x over previous
; __device__ __forceinline__ float ssq4(f32x4 v) { return (v[0] * v[0] + v[1] * v[1]) + (v[2] * v[2] + v[3] * v[3]); }
; __device__ __forceinline__ void p0b_rows(const Params& a) {
;     ...
;     for (int t = t_lo; t < t_hi; t += 2) {
;         const int b = batch_of(t);
;         if (b != bcur) { bcur = b;
; #pragma unroll
;             for (int j = 0; j < 4; ++j) { const int c = 4 * lane + 256 * j; const f32x4 g = *(const f32x4*)(a.in[I_GMIXPRE] + c), sc = *(const f32x4*)(mod + b * 6144 + 1024 + c);
;                 A0[j] = g * (sc + 1.0f); S1[j] = *(const f32x4*)(mod + b * 6144 + c); } }
;         const f32x4* xr = (const f32x4*)xrow_ptr(a, t) + lane; f32x4 v[2][4]; float s0 = 0.f, s1 = 0.f;
; #pragma unroll
;         for (int j = 0; j < 4; ++j) { v[0][j] = xr[64 * j]; v[1][j] = xr[256 + 64 * j]; }
; #pragma unroll
;         for (int j = 0; j < 4; ++j) { s0 += ssq4(v[0][j]); s1 += ssq4(v[1][j]); }
;         wave_sum2(s0, s1);
.LBB0_186:
	s_add_i32 s0, s8, 0xffff0000
	s_cmp_lt_i32 s8, 0x10000
	s_cselect_b32 s1, s9, 0
	s_cselect_b32 s0, s8, s0
	s_cselect_b32 s2, s37, s39
	s_cselect_b32 s3, s36, s38
	s_lshl_b64 s[0:1], s[0:1], 12
	s_add_u32 s0, s3, s0
	s_addc_u32 s1, s2, s1
	global_load_dwordx4 v[60:63], v64, s[0:1] nt
	global_load_dwordx4 v[52:55], v64, s[0:1] offset:1024 nt
	global_load_dwordx4 v[36:39], v64, s[0:1] offset:3072 nt
	global_load_dwordx4 v[44:47], v64, s[0:1] offset:2048 nt
	v_lshl_add_u64 v[32:33], s[0:1], 0, v[64:65]
	v_add_co_u32_e32 v82, vcc, s14, v32
	s_add_u32 s8, s8, 2
	s_nop 0
	v_addc_co_u32_e32 v83, vcc, 0, v33, vcc
	global_load_dwordx4 v[56:59], v[82:83], off nt
	global_load_dwordx4 v[48:51], v[82:83], off offset:1024 nt
	global_load_dwordx4 v[32:35], v[82:83], off offset:3072 nt
	global_load_dwordx4 v[40:43], v[82:83], off offset:2048 nt
	s_addc_u32 s9, s9, 0
	s_cmp_lt_i32 s8, s4
	s_waitcnt vmcnt(7)
	v_pk_mul_f32 v[82:83], v[62:63], v[62:63]
	v_pk_mul_f32 v[84:85], v[60:61], v[60:61]
	s_waitcnt vmcnt(6)
	v_pk_mul_f32 v[86:87], v[54:55], v[54:55]
	v_pk_mul_f32 v[88:89], v[52:53], v[52:53]
	s_waitcnt vmcnt(4)
	v_mul_f32_e32 v90, v45, v45
	v_mul_f32_e32 v92, v47, v47
	v_pk_mov_b32 v[94:95], v[84:85], v[82:83] op_sel:[1,0]
	v_mov_b32_e32 v85, v83
	v_pk_mov_b32 v[82:83], v[88:89], v[86:87] op_sel:[1,0]
	v_mov_b32_e32 v89, v87
	v_pk_fma_f32 v[86:87], v[44:45], v[44:45], v[90:91] op_sel_hi:[1,1,0]
	v_pk_fma_f32 v[90:91], v[46:47], v[46:47], v[92:93] op_sel_hi:[1,1,0]
	v_pk_add_f32 v[84:85], v[94:95], v[84:85]
	s_waitcnt vmcnt(3)
	v_pk_mul_f32 v[92:93], v[58:59], v[58:59]
	v_pk_mul_f32 v[94:95], v[56:57], v[56:57]
	v_pk_add_f32 v[82:83], v[82:83], v[88:89]
	s_waitcnt vmcnt(2)
	v_pk_mul_f32 v[88:89], v[50:51], v[50:51]
	v_pk_mul_f32 v[96:97], v[48:49], v[48:49]
	v_mul_f32_e32 v99, v36, v36
	v_mul_f32_e32 v101, v37, v37
	v_mul_f32_e32 v98, v38, v38
	v_mul_f32_e32 v100, v39, v39
	v_pk_mov_b32 v[102:103], v[94:95], v[92:93] op_sel:[1,0]
	v_mov_b32_e32 v95, v93
	v_pk_mov_b32 v[92:93], v[96:97], v[88:89] op_sel:[1,0]
	v_mov_b32_e32 v97, v89
	v_pk_add_f32 v[84:85], v[84:85], v[84:85] op_sel:[0,1] op_sel_hi:[1,0]
	v_pk_add_f32 v[82:83], v[82:83], v[82:83] op_sel:[0,1] op_sel_hi:[1,0]
	v_mov_b32_e32 v87, v98
	v_mov_b32_e32 v91, v100
	s_waitcnt vmcnt(0)
	v_mul_f32_e32 v98, v41, v41
	v_mul_f32_e32 v100, v43, v43
	v_pk_add_f32 v[94:95], v[102:103], v[94:95]
	v_pk_add_f32 v[92:93], v[92:93], v[96:97]
	v_mov_b32_e32 v85, v99
	v_mov_b32_e32 v83, v101
	v_mul_f32_e32 v104, v32, v32
	v_mul_f32_e32 v105, v33, v33
	v_mul_f32_e32 v106, v34, v34
	v_mul_f32_e32 v107, v35, v35
	v_pk_add_f32 v[86:87], v[86:87], v[90:91]
	v_pk_fma_f32 v[88:89], v[40:41], v[40:41], v[98:99] op_sel_hi:[1,1,0]
	v_pk_fma_f32 v[90:91], v[42:43], v[42:43], v[100:101] op_sel_hi:[1,1,0]
	v_pk_add_f32 v[82:83], v[84:85], v[82:83]
	v_pk_add_f32 v[84:85], v[94:95], v[94:95] op_sel:[0,1] op_sel_hi:[1,0]
	v_pk_add_f32 v[92:93], v[92:93], v[92:93] op_sel:[0,1] op_sel_hi:[1,0]
	v_mov_b32_e32 v89, v106
	v_mov_b32_e32 v91, v107
	v_pk_add_f32 v[82:83], v[82:83], v[86:87]
	v_mov_b32_e32 v85, v104
	v_mov_b32_e32 v93, v105
	v_pk_add_f32 v[88:89], v[88:89], v[90:91]
	v_add_f32_e32 v86, v82, v83
	v_pk_add_f32 v[82:83], v[84:85], v[92:93]
	ds_bpermute_b32 v84, v70, v86
	v_pk_add_f32 v[82:83], v[82:83], v[88:89]
	s_waitcnt lgkmcnt(0)
	v_add_f32_e32 v84, v86, v84
	v_add_f32_e32 v82, v82, v83
	ds_bpermute_b32 v83, v70, v82
	ds_bpermute_b32 v85, v71, v84
	s_waitcnt lgkmcnt(1)
	v_add_f32_e32 v82, v82, v83
	ds_bpermute_b32 v83, v71, v82
	s_waitcnt lgkmcnt(1)
	v_add_f32_e32 v84, v84, v85
	ds_bpermute_b32 v85, v72, v84
	s_waitcnt lgkmcnt(1)
	v_add_f32_e32 v82, v82, v83
	ds_bpermute_b32 v83, v72, v82
	s_waitcnt lgkmcnt(1)
	v_add_f32_e32 v84, v84, v85
	ds_bpermute_b32 v85, v73, v84
	s_waitcnt lgkmcnt(1)
	v_add_f32_e32 v82, v82, v83
	ds_bpermute_b32 v83, v73, v82
	s_waitcnt lgkmcnt(1)
	v_add_f32_e32 v84, v84, v85
	ds_bpermute_b32 v85, v74, v84
	s_waitcnt lgkmcnt(1)
	v_add_f32_e32 v82, v82, v83
	ds_bpermute_b32 v83, v74, v82
	s_waitcnt lgkmcnt(1)
	v_add_f32_e32 v84, v84, v85
	ds_bpermute_b32 v85, v75, v84
	s_waitcnt lgkmcnt(1)
	v_add_f32_e32 v82, v82, v83
	ds_bpermute_b32 v83, v75, v82
	s_waitcnt lgkmcnt(1)
	v_add_f32_e32 v84, v84, v85
	v_fmamk_f32 v84, v84, 0x3a800000, v80
	v_cmp_gt_f32_e32 vcc, s15, v84
	s_waitcnt lgkmcnt(0)
; __device__ __forceinline__ void st4bf(bf16* p, f32x4 v) { v2u w; w.x = pkbf(v[0], v[1]); w.y = pkbf(v[2], v[3]); *(v2u*)p = w; }
; __device__ __forceinline__ void p0b_rows(const Params& a) {
;     ...
;         const float r0 = 1.0f / sqrtf(s0 * (1.0f / DM) + EPS), r1 = 1.0f / sqrtf(s1 * (1.0f / DM) + EPS);
; #pragma unroll
;         for (int j = 0; j < 4; ++j) { st4bf(HB + (size_t)t * DM + 4 * lane + 256 * j, v[0][j] * r0 * A0[j] + S1[j]); st4bf(HB + (size_t)(t + 1) * DM + 4 * lane + 256 * j, v[1][j] * r1 * A0[j] + S1[j]); }
;     }
	v_add_f32_e32 v82, v82, v83
	v_mul_f32_e32 v83, 0x4f800000, v84
	v_cndmask_b32_e32 v83, v84, v83, vcc
	v_fmamk_f32 v82, v82, 0x3a800000, v80
	v_sqrt_f32_e32 v84, v83
	v_mul_f32_e32 v85, 0x4f800000, v82
	v_cmp_gt_f32_e64 s[0:1], s15, v82
	v_add_u32_e32 v86, -1, v84
	s_nop 0
	v_cndmask_b32_e64 v82, v82, v85, s[0:1]
	v_sqrt_f32_e32 v85, v82
	v_add_u32_e32 v87, 1, v84
	v_fma_f32 v88, -v86, v84, v83
	v_fma_f32 v89, -v87, v84, v83
	v_cmp_ge_f32_e64 s[2:3], 0, v88
	v_add_u32_e32 v88, 1, v85
	s_nop 0
	v_cndmask_b32_e64 v84, v84, v86, s[2:3]
	v_add_u32_e32 v86, -1, v85
	v_cmp_lt_f32_e64 s[2:3], 0, v89
	v_fma_f32 v89, -v88, v85, v82
	s_nop 0
	v_cndmask_b32_e64 v84, v84, v87, s[2:3]
	v_fma_f32 v87, -v86, v85, v82
	v_mul_f32_e32 v90, 0x37800000, v84
	v_cmp_ge_f32_e64 s[2:3], 0, v87
	v_cndmask_b32_e32 v84, v84, v90, vcc
	v_cmp_lt_f32_e32 vcc, 0, v89
	v_cndmask_b32_e64 v85, v85, v86, s[2:3]
	s_nop 0
	v_cndmask_b32_e32 v85, v85, v88, vcc
	v_cmp_class_f32_e32 vcc, v83, v81
	s_nop 1
	v_cndmask_b32_e32 v83, v84, v83, vcc
	v_mul_f32_e32 v84, 0x37800000, v85
	v_div_scale_f32 v86, s[2:3], v83, v83, 1.0
	v_cndmask_b32_e64 v84, v85, v84, s[0:1]
	v_rcp_f32_e32 v85, v86
	v_cmp_class_f32_e64 s[0:1], v82, v81
	v_div_scale_f32 v87, vcc, 1.0, v83, 1.0
	s_nop 0
	v_cndmask_b32_e64 v84, v84, v82, s[0:1]
	v_div_scale_f32 v88, s[0:1], v84, v84, 1.0
	v_fma_f32 v82, -v86, v85, 1.0
	v_rcp_f32_e32 v90, v88
	v_fmac_f32_e32 v85, v82, v85
	v_mul_f32_e32 v82, v87, v85
	v_fma_f32 v92, -v86, v82, v87
	v_fmac_f32_e32 v82, v92, v85
	v_fma_f32 v91, -v88, v90, 1.0
	v_fma_f32 v86, -v86, v82, v87
	v_div_scale_f32 v89, s[0:1], 1.0, v84, 1.0
	v_fmac_f32_e32 v90, v91, v90
	v_div_fmas_f32 v82, v86, v85, v82
	v_div_fixup_f32 v82, v82, v83, 1.0
	v_mul_f32_e32 v83, v89, v90
	v_fma_f32 v85, -v88, v83, v89
	v_fmac_f32_e32 v83, v85, v90
	v_fma_f32 v85, -v88, v83, v89
	s_mov_b64 vcc, s[0:1]
	v_div_fmas_f32 v83, v85, v90, v83
	v_div_fixup_f32 v84, v83, v84, 1.0
	v_pk_mul_f32 v[60:61], v[60:61], v[82:83] op_sel_hi:[1,0]
	v_pk_mul_f32 v[56:57], v[56:57], v[84:85] op_sel_hi:[1,0]
	v_pk_mul_f32 v[52:53], v[52:53], v[82:83] op_sel_hi:[1,0]
	v_pk_mul_f32 v[48:49], v[48:49], v[84:85] op_sel_hi:[1,0]
	v_pk_mul_f32 v[44:45], v[44:45], v[82:83] op_sel_hi:[1,0]
	v_pk_mul_f32 v[40:41], v[40:41], v[84:85] op_sel_hi:[1,0]
	v_pk_mul_f32 v[36:37], v[36:37], v[82:83] op_sel_hi:[1,0]
	v_pk_mul_f32 v[32:33], v[32:33], v[84:85] op_sel_hi:[1,0]
	v_pk_mul_f32 v[62:63], v[62:63], v[82:83] op_sel_hi:[1,0]
	v_pk_fma_f32 v[60:61], v[16:17], v[60:61], v[8:9]
	v_pk_mul_f32 v[58:59], v[58:59], v[84:85] op_sel_hi:[1,0]
	v_pk_fma_f32 v[56:57], v[16:17], v[56:57], v[8:9]
	v_pk_mul_f32 v[54:55], v[54:55], v[82:83] op_sel_hi:[1,0]
	v_pk_fma_f32 v[52:53], v[20:21], v[52:53], v[4:5]
	v_pk_mul_f32 v[50:51], v[50:51], v[84:85] op_sel_hi:[1,0]
	v_pk_fma_f32 v[48:49], v[20:21], v[48:49], v[4:5]
	v_pk_mul_f32 v[46:47], v[46:47], v[82:83] op_sel_hi:[1,0]
	v_pk_fma_f32 v[44:45], v[24:25], v[44:45], v[0:1]
	v_pk_mul_f32 v[42:43], v[42:43], v[84:85] op_sel_hi:[1,0]
	v_pk_fma_f32 v[40:41], v[24:25], v[40:41], v[0:1]
	v_pk_mul_f32 v[38:39], v[38:39], v[82:83] op_sel_hi:[1,0]
	v_pk_fma_f32 v[36:37], v[28:29], v[36:37], v[12:13]
	v_pk_mul_f32 v[34:35], v[34:35], v[84:85] op_sel_hi:[1,0]
	v_pk_fma_f32 v[32:33], v[28:29], v[32:33], v[12:13]
	v_pk_fma_f32 v[62:63], v[18:19], v[62:63], v[10:11]
	v_cvt_pk_bf16_f32 v60, v60, v61
	v_pk_fma_f32 v[58:59], v[18:19], v[58:59], v[10:11]
	v_cvt_pk_bf16_f32 v61, v62, v63
	global_store_dwordx2 v[68:69], v[60:61], off offset:-3584
	v_cvt_pk_bf16_f32 v56, v56, v57
	v_cvt_pk_bf16_f32 v57, v58, v59
	global_store_dwordx2 v[68:69], v[56:57], off offset:-1536
	v_pk_fma_f32 v[54:55], v[22:23], v[54:55], v[6:7]
	v_cvt_pk_bf16_f32 v52, v52, v53
	v_pk_fma_f32 v[50:51], v[22:23], v[50:51], v[6:7]
	v_cvt_pk_bf16_f32 v53, v54, v55
	global_store_dwordx2 v[68:69], v[52:53], off offset:-3072
	v_cvt_pk_bf16_f32 v48, v48, v49
	v_cvt_pk_bf16_f32 v49, v50, v51
	global_store_dwordx2 v[68:69], v[48:49], off offset:-1024
	v_pk_fma_f32 v[46:47], v[26:27], v[46:47], v[2:3]
	v_cvt_pk_bf16_f32 v44, v44, v45
	v_pk_fma_f32 v[42:43], v[26:27], v[42:43], v[2:3]
	v_cvt_pk_bf16_f32 v45, v46, v47
	global_store_dwordx2 v[68:69], v[44:45], off offset:-2560
	v_cvt_pk_bf16_f32 v40, v40, v41
	v_cvt_pk_bf16_f32 v41, v42, v43
	global_store_dwordx2 v[68:69], v[40:41], off offset:-512
	v_pk_fma_f32 v[38:39], v[30:31], v[38:39], v[14:15]
	v_cvt_pk_bf16_f32 v36, v36, v37
	v_pk_fma_f32 v[34:35], v[30:31], v[34:35], v[14:15]
	v_cvt_pk_bf16_f32 v37, v38, v39
	global_store_dwordx2 v[68:69], v[36:37], off offset:-2048
	v_cvt_pk_bf16_f32 v32, v32, v33
	v_cvt_pk_bf16_f32 v33, v34, v35
	global_store_dwordx2 v[68:69], v[32:33], off
	v_lshl_add_u64 v[68:69], v[68:69], 0, s[10:11]
	s_cbranch_scc0 .LBB0_189
